# GEMM1: staged LDS half-tile image = 128-byte rows with XOR-swizzled 16-byte chunks, every LDS-DMA instruction fetches 8 whole cache lines
# speedup vs baseline: 1.0019x; 1.0019x over previous
; template <class Epi, class Sched, bool ALIGN_EPI = false, bool SP2 = false>
; __device__ __forceinline__ void gemm_phase(PG8_LAS unsigned char* lds, const Gemm g, const Sched& S, const Epi& E) {
;     ...
;     for (int i = 0; i < 2; ++i) { int R, C; stage_rc(tid * 16 + i * 8192, R, C); const int Rb = Epi::PERM ? ((R & ~31) + perm32(R & 31)) : R;
;         voffA[i] = (unsigned)(R * K + C) * 2u; voffB[i] = (unsigned)(Rb * K + C) * 2u; }
; __global__ void __launch_bounds__(NTHREADS, 2) fwd_kernel(Params p) {
;     ...
;         pg8::Gemm g{(const bf16_t*)(ws + WS_XB), (const bf16_t*)(ws + WS_WIN), T, N1, DM}; pg8::StaticOrder S; S.init(T, N1, G, cid);
;         EpiProj E{(bf16_t*)(ws + WS_NAQKV), (bf16_t*)(ws + WS_MLQK), (bf16_t*)(ws + WS_MLV), (bf16_t*)(ws + WS_MLO), (bf16_t*)(ws + WS_MG), (float*)(ws + WS_GATES)};
;         pg8::gemm_phase<EpiProj, pg8::StaticOrder, true, true>(ring, g, S, E);
.LBB0_121:
	v_readlane_b32 s0, v246, 12
	v_readlane_b32 s1, v246, 13
	s_cmp_lt_i32 s0, 2
	v_readlane_b32 s2, v246, 14
	v_readlane_b32 s3, v246, 15
	s_cselect_b64 s[0:1], -1, 0
	s_and_b64 s[2:3], s[0:1], s[4:5]
	s_andn2_b64 vcc, exec, s[2:3]
	s_cbranch_vccnz .LBB0_158
	v_readlane_b32 s2, v246, 0
	s_cmpk_gt_i32 s2, 0x15ff
	v_readfirstlane_b32 s7, v144
	v_readlane_b32 s3, v246, 1
	s_cbranch_scc1 .LBB0_158
	v_lshrrev_b32_e32 v238, 3, v144
	v_and_b32_e32 v239, 7, v144
	v_and_b32_e32 v240, 7, v238
	v_xor_b32_e32 v239, v239, v240
	v_lshlrev_b32_e32 v239, 4, v239
	v_lshl_or_b32 v240, v238, 12, v239
	v_add_u32_e32 v241, 0x40000, v240
	v_and_b32_e32 v242, 31, v238
	v_bfe_u32 v243, v242, 2, 2
	v_lshlrev_b32_e32 v243, 3, v243
	v_lshrrev_b32_e32 v230, 4, v242
	v_lshl_or_b32 v243, v230, 2, v243
	v_and_b32_e32 v230, 3, v242
	v_or_b32_e32 v243, v243, v230
	v_and_b32_e32 v230, 32, v238
	v_or_b32_e32 v243, v243, v230
	v_lshl_or_b32 v238, v243, 12, v239
	v_add_u32_e32 v239, 0x40000, v238
	v_readlane_b32 s36, v246, 10
	v_readlane_b32 s37, v246, 11
	v_readlane_b32 s38, v246, 0
	v_readfirstlane_b32 s39, v144
	v_and_b32_e32 v0, 15, v144
	v_bfe_u32 v1, v144, 4, 2
	v_lshlrev_b32_e32 v2, 6, v0
	v_lshlrev_b32_e32 v0, 12, v0
	v_lshl_or_b32 v0, v1, 4, v0
	v_lshl_or_b32 v2, v1, 4, v2
	s_lshr_b32 s39, s39, 6
	s_lshl_b32 s38, s38, 3
	s_add_i32 s38, s38, s39
	s_lshl_b32 s40, s34, 3
	s_add_u32 s42, s36, 0x2d00000
	s_addc_u32 s43, s37, 0

; #define PG8_STAGE(bufoff, gbase, voff) do { _Pragma("unroll") for (int _i = 0; _i < 2; ++_i) \
;         __builtin_amdgcn_global_load_lds((const unsigned*)((const char*)(gbase) + (voff)[_i]), (PG8_LAS unsigned*)(lds + (bufoff) + ldsw + _i * 8192), 16, 0, 0); } while (0)
; #define PG8_WAIT_V(n) asm volatile("s_waitcnt vmcnt(" #n ")" ::: "memory")
; #define PG8_BAR __builtin_amdgcn_s_barrier()
;     __device__ bool next(int i, pg8::Unit& u) const { if (!base.next(i >> 1, u)) return false; u.seg = i & 1; return true; }
; template <class Epi, class Sched, bool ALIGN_EPI = false, bool SP2 = false>
; __device__ __forceinline__ void gemm_phase(PG8_LAS unsigned char* lds, const Gemm g, const Sched& S, const Epi& E) {
;     ...
;     for (int i = 0; i < 2; ++i) { int R, C; stage_rc(tid * 16 + i * 8192, R, C); const int Rb = Epi::PERM ? ((R & ~31) + perm32(R & 31)) : R;
;         voffA[i] = (unsigned)(R * K + C) * 2u; voffB[i] = (unsigned)(Rb * K + C) * 2u; }
;     const size_t kstep = (size_t)(BK * 2);
;     const size_t hstep = (size_t)HALF * K * 2;
;     const size_t tstep = 2 * hstep;
;     const unsigned ldsw = (unsigned)wid * 1024u;
;     const int aoff = lds_byte(wr * 64 + fr, fq * 8), boff = lds_byte(wc * 32 + fr, fq * 8);
;     ...
;     Unit cur, nxt; int ui = 0;
;     if (!S.next(0, cur)) return;
;     f32x4 acc[2][2][4][2];
; #pragma unroll
;     for (int a = 0; a < 2; ++a)
; #pragma unroll
;         for (int b = 0; b < 2; ++b)
; #pragma unroll
;             for (int m = 0; m < 4; ++m)
; #pragma unroll
;                 for (int n = 0; n < 2; ++n) acc[a][b][m][n] = (f32x4){0.f, 0.f, 0.f, 0.f};
;     bf16x8 At[4][2], B0[2][2], B1[2][2];
;     const char* cA = (const char*)(cur.seg ? g.A2 : g.A) + (size_t)cur.pm * tstep; const char* cB = (const char*)(cur.seg ? g.Bt2 : g.Bt) + (size_t)cur.pn * tstep;
;     S.a_ready(cur);
;     if constexpr (SP2) {
;         PG8_STAGE(PG8_SB(0, 0), cB, voffB); PG8_STAGE(PG8_SB(0, 1), cB + hstep, voffB); PG8_STAGE(PG8_SA(0, 0), cA, voffA); PG8_STAGE(PG8_SA(0, 1), cA + hstep, voffA);
;         if (wr == 1) PG8_BAR;
;         PG8_WAIT_V(2); PG8_BAR;
;         PG8_STAGE(PG8_SB(1, 0), cB + kstep, voffB); PG8_STAGE(PG8_SA(1, 0), cA + kstep, voffA); PG8_STAGE(PG8_SB(1, 1), cB + hstep + kstep, voffB);
;         PG8_WAIT_V(6); PG8_BAR;
.Lgate_done:
	v_lshrrev_b32_e32 v0, 5, v144
	v_lshrrev_b32_e32 v2, 1, v144
	v_readlane_b32 s2, v246, 10
	v_and_b32_e32 v0, 4, v0
	v_bfe_u32 v1, v144, 2, 2
	v_and_b32_e32 v2, 24, v2
	v_readlane_b32 s3, v246, 11
	s_add_u32 s35, s2, 0x8800000
	v_or3_b32 v0, v0, v1, v2
	v_lshlrev_b32_e32 v1, 4, v144
	s_addc_u32 s54, s3, 0
	s_waitcnt vmcnt(1)
	v_add_u32_e32 v8, 0x2000, v1
	s_add_u32 s55, s2, 0x100000
	v_lshrrev_b32_e32 v2, 7, v8
	s_movk_i32 s2, 0xe0
	v_and_b32_e32 v4, 32, v144
	v_and_or_b32 v3, v2, s2, v0
	v_bitop3_b32 v9, v1, v4, 48 bitop3:0x6c
	v_and_b32_e32 v10, 64, v144
	v_bfe_u32 v11, v144, 2, 4
	s_movk_i32 s2, 0xf0
	v_or_b32_e32 v1, v9, v10
	v_and_or_b32 v2, v2, s2, v11
	v_lshl_or_b32 v130, v2, 12, v1
	v_mov_b32_e32 v130, v241
	v_lshrrev_b32_e32 v2, 3, v144
	s_movk_i32 s2, 0x60
	v_and_or_b32 v0, v2, s2, v0
	s_movk_i32 s2, 0x70
	s_addc_u32 s56, s3, 0
	v_lshl_or_b32 v132, v0, 12, v1
	v_mov_b32_e32 v132, v238
	v_and_or_b32 v0, v2, s2, v11
	v_readlane_b32 s2, v246, 0
	s_ashr_i32 s58, s2, 31
	s_mov_b32 s4, s2
	s_lshr_b32 s2, s58, 29
	v_readlane_b32 s3, v246, 1
	s_add_i32 s2, s4, s2
	s_lshr_b32 s12, s7, 6
	s_ashr_i32 s3, s2, 3
	s_and_b32 s2, s2, -8
	s_lshr_b32 s14, s7, 8
	s_lshl_b32 s57, s12, 10
	s_sub_i32 s2, s4, s2
	s_cmp_lt_i32 s2, 0
	s_movk_i32 s59, 0x2c1
	s_cselect_b32 s4, s59, 0x2c0
	s_mul_i32 s2, s2, s4
	s_add_i32 s2, s2, s3
	s_mul_hi_i32 s3, s2, 0xba2e8ba4
	s_add_i32 s3, s3, s2
	s_lshr_b32 s4, s3, 31
	s_ashr_i32 s3, s3, 8
	s_add_i32 s3, s3, s4
	s_lshl_b32 s4, s3, 3
	s_mulk_i32 s3, 0x160
	s_sub_i32 s2, s2, s3
	s_sext_i32_i16 s3, s2
	s_bfe_u32 s3, s3, 0x3001c
	s_add_i32 s3, s2, s3
	s_sext_i32_i16 s5, s3
	s_and_b32 s3, s3, 0xfff8
	s_sub_i32 s2, s2, s3
	s_sext_i32_i16 s2, s2
	s_lshr_b32 s6, s5, 3
	s_add_i32 s46, s4, s2
	s_ashr_i32 s47, s46, 31
	s_bfe_i64 s[4:5], s[6:7], 0x100000
	s_lshl_b64 s[2:3], s[46:47], 20
	s_lshl_b64 s[4:5], s[4:5], 20
	s_add_u32 s50, s55, s4
	s_addc_u32 s51, s56, s5
	s_add_i32 s60, s57, 0
	s_add_i32 m0, s60, 0x10000
	v_lshl_or_b32 v128, v3, 12, v1
	v_mov_b32_e32 v128, v239
	global_load_lds_dwordx4 v132, s[50:51]
	s_add_i32 m0, s60, 0x12000
	s_add_u32 s4, s50, 0x80000
	global_load_lds_dwordx4 v128, s[50:51]
	s_addc_u32 s5, s51, 0
	s_add_i32 m0, s60, 0x14000
	v_lshl_or_b32 v134, v0, 12, v1
	v_mov_b32_e32 v134, v240
	global_load_lds_dwordx4 v132, s[4:5]
	s_add_i32 m0, s60, 0x16000
	s_add_u32 s48, s35, s2
	s_addc_u32 s49, s54, s3
	s_add_i32 s61, s60, 0x2000
	global_load_lds_dwordx4 v128, s[4:5]
	s_mov_b32 m0, s60
	s_add_u32 s2, s48, 0x80000
	global_load_lds_dwordx4 v134, s[48:49]
	s_mov_b32 m0, s61
	s_addc_u32 s3, s49, 0
	s_add_i32 s62, s60, 0x4000
	global_load_lds_dwordx4 v130, s[48:49]
	s_mov_b32 m0, s62
	s_add_i32 s63, s60, 0x6000
	global_load_lds_dwordx4 v134, s[2:3]
	s_mov_b32 m0, s63
	v_mov_b32_e32 v133, 0
	global_load_lds_dwordx4 v130, s[2:3]
	v_mov_b32_e32 v129, v133
	v_mov_b32_e32 v135, v133
	v_mov_b32_e32 v131, v133
	s_cmp_eq_u32 s14, 1
	s_mov_b32 s64, 0
	v_lshl_add_u64 v[6:7], s[50:51], 0, v[132:133]
	v_lshl_add_u64 v[4:5], s[50:51], 0, v[128:129]
	v_lshl_add_u64 v[0:1], s[48:49], 0, v[134:135]
	s_cselect_b64 s[2:3], -1, 0
	s_cmp_lg_u32 s14, 1
	v_lshl_add_u64 v[2:3], s[48:49], 0, v[130:131]
	s_cbranch_scc1 .LBB0_125
	s_barrier
.LBB0_125:
	v_readlane_b32 s38, v246, 10
	v_readlane_b32 s39, v246, 11
	s_add_u32 s4, s38, 0x10800000
	s_addc_u32 s5, s39, 0
	s_add_u32 s8, s38, 0x1c800000
	s_addc_u32 s9, s39, 0
	s_add_u32 s10, s38, 0x24800000
	s_addc_u32 s11, s39, 0
	s_and_b32 s33, s12, 3
	s_mov_b64 s[12:13], 0x80
	s_add_i32 m0, s60, 0x18000
	v_lshl_add_u64 v[6:7], v[6:7], 0, s[12:13]
	s_lshl_b32 s15, s14, 13
	s_lshl_b32 s36, s33, 12
	s_waitcnt vmcnt(2)
	s_barrier
	global_load_lds_dwordx4 v[6:7], off
	v_lshl_add_u64 v[4:5], v[4:5], 0, s[12:13]
	s_add_i32 m0, s60, 0x1a000
	s_add_i32 s65, s60, 0x8000
	s_add_i32 s66, s60, 0xa000
	global_load_lds_dwordx4 v[4:5], off
	v_lshl_add_u64 v[0:1], v[0:1], 0, s[12:13]
	s_mov_b32 m0, s65
	s_add_u32 s18, s50, 0x80080
	global_load_lds_dwordx4 v[0:1], off
	v_lshl_add_u64 v[0:1], v[2:3], 0, s[12:13]
	s_mov_b32 m0, s66
	s_addc_u32 s19, s51, 0
	global_load_lds_dwordx4 v[0:1], off
	s_add_i32 m0, s60, 0x1c000
	v_lshl_add_u64 v[0:1], s[18:19], 0, v[132:133]
	global_load_lds_dwordx4 v[0:1], off
	v_lshl_add_u64 v[0:1], s[18:19], 0, v[128:129]
	s_add_i32 m0, s60, 0x1e000
	v_lshlrev_b32_e32 v4, 2, v144
	global_load_lds_dwordx4 v[0:1], off
	v_lshrrev_b32_e32 v0, 4, v144
	v_and_b32_e32 v0, 3, v0
	v_and_b32_e32 v1, 15, v144
	v_lshlrev_b32_e32 v3, 4, v0
	v_lshl_or_b32 v145, s14, 6, v1
	v_lshl_or_b32 v1, v1, 6, v3
	v_and_b32_e32 v4, 32, v4
	s_sext_i32_i16 s70, s6
	v_bitop3_b32 v5, v1, s15, v4 bitop3:0xde
	v_lshlrev_b32_e32 v1, 6, v144
	s_movk_i32 s6, 0x3c0
	s_cmpk_lt_u32 s7, 0x100
	v_and_or_b32 v1, v1, s6, v3
	s_cselect_b64 s[14:15], -1, 0
	s_cmp_eq_u32 s33, 0
	v_lshlrev_b32_e32 v2, 3, v0
	v_bitop3_b32 v154, s36, v1, v4 bitop3:0xf6
	s_cselect_b64 s[6:7], -1, 0
	v_cmp_gt_u32_e32 vcc, 2, v0
	v_lshlrev_b32_e32 v0, 5, v0
	v_mov_b32_e32 v1, v133
	s_and_b64 s[18:19], s[6:7], vcc
	v_lshl_add_u64 v[0:1], s[38:39], 0, v[0:1]
	s_mov_b64 s[6:7], 0x7f00000
	v_lshl_add_u64 v[136:137], v[0:1], 0, s[6:7]
	v_lshlrev_b32_e32 v0, 9, v144
	v_and_b32_e32 v0, 0x70000, v0
	v_lshlrev_b32_e32 v1, 12, v11
	v_or3_b32 v0, v9, v0, v1
	v_add_u32_e32 v138, v0, v10
	v_mov_b32_e32 v138, v240
	v_lshlrev_b32_e32 v0, 5, v8
	s_waitcnt vmcnt(6)
	v_and_b32_e32 v0, 0xf0000, v0
	v_or3_b32 v0, v9, v0, v1
	s_add_i32 s68, 0, 0x10000
	s_add_i32 s69, 0, 0x14000
	v_lshl_or_b32 v155, s33, 5, v2
	s_ashr_i32 s67, s34, 31
	v_mov_b32_e32 v139, v133
	v_add_u32_e32 v140, v0, v10
	v_mov_b32_e32 v140, v241
	v_mov_b32_e32 v141, v133
	v_mov_b64_e32 v[142:143], 0x1600
	v_mov_b64_e32 v[146:147], 0x15ff
	v_add_u32_e32 v156, s68, v154
	v_add_u32_e32 v157, s69, v154
	v_add_u32_e32 v158, 0, v5
	v_and_b32_e32 v230, 15, v144
	v_bfe_u32 v231, v144, 4, 2
	v_and_b32_e32 v232, 7, v230
	v_xor_b32_e32 v231, v231, v232
	v_lshlrev_b32_e32 v231, 4, v231
	v_lshl_or_b32 v231, v230, 7, v231
	v_lshrrev_b32_e32 v232, 8, v144
	v_lshl_or_b32 v158, v232, 13, v231
	v_xor_b32_e32 v242, 64, v158
	v_bfe_u32 v232, v144, 6, 2
	v_lshl_or_b32 v156, v232, 12, v231
	v_add_u32_e32 v156, 0x10000, v156
	v_xor_b32_e32 v157, 64, v156
	v_mov_b32_e32 v160, 0x437f0000
	s_barrier
	s_branch .LBB0_128

; #define PG8_STAGE(bufoff, gbase, voff) do { _Pragma("unroll") for (int _i = 0; _i < 2; ++_i) \
;         __builtin_amdgcn_global_load_lds((const unsigned*)((const char*)(gbase) + (voff)[_i]), (PG8_LAS unsigned*)(lds + (bufoff) + ldsw + _i * 8192), 16, 0, 0); } while (0)
; #define PG8_LDA(dst, b, h) do { _Pragma("unroll") for (int m = 0; m < 4; ++m) _Pragma("unroll") for (int k = 0; k < 2; ++k) dst[m][k] = *(const PG8_LAS bf16x8*)(lds + PG8_SA(b, h) + aoff + m * 2048 + k * 1024); } while (0)
; #define PG8_LDB(dst, b, h) do { _Pragma("unroll") for (int n = 0; n < 2; ++n) _Pragma("unroll") for (int k = 0; k < 2; ++k) dst[n][k] = *(const PG8_LAS bf16x8*)(lds + PG8_SB(b, h) + boff + n * 2048 + k * 1024); } while (0)
; #define PG8_MMA(ai, bj, At, Bt) do { __builtin_amdgcn_s_setprio(1); _Pragma("unroll") for (int m = 0; m < 4; ++m) _Pragma("unroll") for (int n = 0; n < 2; ++n) _Pragma("unroll") for (int k = 0; k < 2; ++k) \
;         acc[ai][bj][m][n] = __builtin_amdgcn_mfma_f32_16x16x32_bf16(Bt[n][k], At[m][k], acc[ai][bj][m][n], 0, 0, 0); __builtin_amdgcn_s_setprio(0); } while (0)
; #define PG8_WAIT_V(n) asm volatile("s_waitcnt vmcnt(" #n ")" ::: "memory")
; #define PG8_WAIT_L(n) asm volatile("s_waitcnt lgkmcnt(" #n ")" ::: "memory")
; #define PG8_BAR __builtin_amdgcn_s_barrier()
; #define PG8_SCHED __builtin_amdgcn_sched_barrier(0)
; template <class Epi, class Sched, bool ALIGN_EPI = false, bool SP2 = false>
; __device__ __forceinline__ void gemm_phase(PG8_LAS unsigned char* lds, const Gemm g, const Sched& S, const Epi& E) {
;     ...
;             PG8_LDB(B0, 0, 0); PG8_LDB(B1, 0, 1); PG8_SCHED; PG8_LDA(At, 0, 0); PG8_STAGE(PG8_SA(1, 1), a1 + hstep, voffA);
;             PG8_WAIT_V(8); PG8_WAIT_L(0); PG8_BAR; PG8_MMA(0, 0, At, B0); PG8_MMA(0, 1, At, B1); PG8_BAR; PG8_SCHED;
;             PG8_LDA(At, 0, 1); PG8_STAGE(PG8_SB(0, 0), b2, voffB); PG8_STAGE(PG8_SB(0, 1), b2 + hstep, voffB); PG8_STAGE(PG8_SA(0, 0), a2, voffA);
;             PG8_WAIT_V(8); PG8_WAIT_L(0); PG8_BAR; PG8_MMA(1, 0, At, B0); PG8_MMA(1, 1, At, B1); PG8_BAR; PG8_SCHED;
.LBB0_131:
	ds_read_b128 v[148:151], v156
	ds_read_b128 v[162:165], v157
	ds_read_b128 v[166:169], v156 offset:2048
	ds_read_b128 v[170:173], v157 offset:2048
	ds_read_b128 v[174:177], v156 offset:16384
	ds_read_b128 v[178:181], v157 offset:16384
	ds_read_b128 v[182:185], v156 offset:18432
	ds_read_b128 v[186:189], v157 offset:18432
	s_add_u32 s36, s48, 0xfff80080
	s_addc_u32 s37, s49, -1
	s_cmp_eq_u32 s73, 28
	s_cselect_b32 s53, s33, s37
	s_cselect_b32 s52, s41, s36
	s_cselect_b32 s51, s39, s72
	s_cselect_b32 s50, s47, s71
	v_lshl_add_u64 v[152:153], s[48:49], 0, v[138:139]
	s_add_i32 m0, s60, 0xc000
	ds_read_b128 v[190:193], v158
	ds_read_b128 v[194:197], v242
	ds_read_b128 v[198:201], v158 offset:2048
	ds_read_b128 v[202:205], v242 offset:2048
	ds_read_b128 v[206:209], v158 offset:4096
	ds_read_b128 v[210:213], v242 offset:4096
	ds_read_b128 v[214:217], v158 offset:6144
	ds_read_b128 v[218:221], v242 offset:6144
	global_load_lds_dwordx4 v[152:153], off
	v_lshl_add_u64 v[152:153], s[48:49], 0, v[140:141]
	s_add_i32 m0, s60, 0xe000
	s_nop 0
	global_load_lds_dwordx4 v[152:153], off
	s_waitcnt vmcnt(8)
	s_waitcnt lgkmcnt(0)
	s_barrier
	s_setprio 1
	s_waitcnt lgkmcnt(0)
	v_mfma_f32_16x16x32_bf16 v[76:79], v[148:151], v[190:193], v[76:79]
	v_mfma_f32_16x16x32_bf16 v[72:75], v[166:169], v[190:193], v[72:75]
	v_mfma_f32_16x16x32_bf16 v[68:71], v[148:151], v[198:201], v[68:71]
	v_mfma_f32_16x16x32_bf16 v[64:67], v[166:169], v[198:201], v[64:67]
	v_mfma_f32_16x16x32_bf16 v[60:63], v[148:151], v[206:209], v[60:63]
	v_mfma_f32_16x16x32_bf16 v[52:55], v[166:169], v[206:209], v[52:55]
	v_mfma_f32_16x16x32_bf16 v[44:47], v[148:151], v[214:217], v[44:47]
	v_mfma_f32_16x16x32_bf16 v[40:43], v[166:169], v[214:217], v[40:43]
	v_mfma_f32_16x16x32_bf16 v[76:79], v[162:165], v[194:197], v[76:79]
	v_mfma_f32_16x16x32_bf16 v[72:75], v[170:173], v[194:197], v[72:75]
	v_mfma_f32_16x16x32_bf16 v[68:71], v[162:165], v[202:205], v[68:71]
	v_mfma_f32_16x16x32_bf16 v[64:67], v[170:173], v[202:205], v[64:67]
	v_mfma_f32_16x16x32_bf16 v[60:63], v[162:165], v[210:213], v[60:63]
	v_mfma_f32_16x16x32_bf16 v[52:55], v[170:173], v[210:213], v[52:55]
	v_mfma_f32_16x16x32_bf16 v[44:47], v[162:165], v[218:221], v[44:47]
	v_mfma_f32_16x16x32_bf16 v[40:43], v[170:173], v[218:221], v[40:43]
	s_setprio 0
	s_setprio 1
	v_mfma_f32_16x16x32_bf16 v[124:127], v[174:177], v[190:193], v[124:127]
	v_mfma_f32_16x16x32_bf16 v[120:123], v[182:185], v[190:193], v[120:123]
	v_mfma_f32_16x16x32_bf16 v[116:119], v[174:177], v[198:201], v[116:119]
	v_mfma_f32_16x16x32_bf16 v[112:115], v[182:185], v[198:201], v[112:115]
	v_mfma_f32_16x16x32_bf16 v[108:111], v[174:177], v[206:209], v[108:111]
	v_mfma_f32_16x16x32_bf16 v[104:107], v[182:185], v[206:209], v[104:107]
	v_mfma_f32_16x16x32_bf16 v[100:103], v[174:177], v[214:217], v[100:103]
	v_mfma_f32_16x16x32_bf16 v[96:99], v[182:185], v[214:217], v[96:99]
	v_mfma_f32_16x16x32_bf16 v[124:127], v[178:181], v[194:197], v[124:127]
	v_mfma_f32_16x16x32_bf16 v[120:123], v[186:189], v[194:197], v[120:123]
	v_mfma_f32_16x16x32_bf16 v[116:119], v[178:181], v[202:205], v[116:119]
	v_mfma_f32_16x16x32_bf16 v[112:115], v[186:189], v[202:205], v[112:115]
	v_mfma_f32_16x16x32_bf16 v[108:111], v[178:181], v[210:213], v[108:111]
	v_mfma_f32_16x16x32_bf16 v[104:107], v[186:189], v[210:213], v[104:107]
	v_mfma_f32_16x16x32_bf16 v[100:103], v[178:181], v[218:221], v[100:103]
	v_mfma_f32_16x16x32_bf16 v[96:99], v[186:189], v[218:221], v[96:99]
	s_setprio 0
	s_barrier
	s_add_i32 s36, s68, s57
	v_lshl_add_u64 v[152:153], s[50:51], 0, v[132:133]
	s_mov_b32 m0, s36
	ds_read_b128 v[190:193], v158 offset:16384
	ds_read_b128 v[194:197], v242 offset:16384
	ds_read_b128 v[198:201], v158 offset:18432
	ds_read_b128 v[202:205], v242 offset:18432
	ds_read_b128 v[206:209], v158 offset:20480
	ds_read_b128 v[210:213], v242 offset:20480
	ds_read_b128 v[214:217], v158 offset:22528
	ds_read_b128 v[218:221], v242 offset:22528
	global_load_lds_dwordx4 v[152:153], off
	s_add_i32 m0, s36, 0x2000
	s_add_u32 s74, s50, 0x80000
	v_lshl_add_u64 v[222:223], s[50:51], 0, v[128:129]
	s_addc_u32 s75, s51, 0
	s_add_i32 s36, s69, s57
	global_load_lds_dwordx4 v[222:223], off
	v_lshl_add_u64 v[224:225], s[74:75], 0, v[132:133]
	s_mov_b32 m0, s36
	v_lshl_add_u64 v[226:227], s[52:53], 0, v[130:131]
	global_load_lds_dwordx4 v[224:225], off
	v_lshl_add_u64 v[224:225], s[74:75], 0, v[128:129]
	s_add_i32 m0, s36, 0x2000
	s_nop 0
	global_load_lds_dwordx4 v[224:225], off
	v_lshl_add_u64 v[224:225], s[52:53], 0, v[134:135]
	s_mov_b32 m0, s60
	s_nop 0
	global_load_lds_dwordx4 v[224:225], off
	s_mov_b32 m0, s61
	s_nop 0
	global_load_lds_dwordx4 v[226:227], off
	s_waitcnt vmcnt(8)
	s_waitcnt lgkmcnt(0)
	s_barrier
; #define PG8_STAGE(bufoff, gbase, voff) do { _Pragma("unroll") for (int _i = 0; _i < 2; ++_i) \
;         __builtin_amdgcn_global_load_lds((const unsigned*)((const char*)(gbase) + (voff)[_i]), (PG8_LAS unsigned*)(lds + (bufoff) + ldsw + _i * 8192), 16, 0, 0); } while (0)
; #define PG8_LDA(dst, b, h) do { _Pragma("unroll") for (int m = 0; m < 4; ++m) _Pragma("unroll") for (int k = 0; k < 2; ++k) dst[m][k] = *(const PG8_LAS bf16x8*)(lds + PG8_SA(b, h) + aoff + m * 2048 + k * 1024); } while (0)
; #define PG8_LDB(dst, b, h) do { _Pragma("unroll") for (int n = 0; n < 2; ++n) _Pragma("unroll") for (int k = 0; k < 2; ++k) dst[n][k] = *(const PG8_LAS bf16x8*)(lds + PG8_SB(b, h) + boff + n * 2048 + k * 1024); } while (0)
; #define PG8_MMA(ai, bj, At, Bt) do { __builtin_amdgcn_s_setprio(1); _Pragma("unroll") for (int m = 0; m < 4; ++m) _Pragma("unroll") for (int n = 0; n < 2; ++n) _Pragma("unroll") for (int k = 0; k < 2; ++k) \
;         acc[ai][bj][m][n] = __builtin_amdgcn_mfma_f32_16x16x32_bf16(Bt[n][k], At[m][k], acc[ai][bj][m][n], 0, 0, 0); __builtin_amdgcn_s_setprio(0); } while (0)
; #define PG8_WAIT_V(n) asm volatile("s_waitcnt vmcnt(" #n ")" ::: "memory")
; #define PG8_WAIT_L(n) asm volatile("s_waitcnt lgkmcnt(" #n ")" ::: "memory")
; #define PG8_BAR __builtin_amdgcn_s_barrier()
; #define PG8_SCHED __builtin_amdgcn_sched_barrier(0)
; template <class Epi, class Sched, bool ALIGN_EPI = false, bool SP2 = false>
; __device__ __forceinline__ void gemm_phase(PG8_LAS unsigned char* lds, const Gemm g, const Sched& S, const Epi& E) {
;     ...
;             PG8_WAIT_V(8); PG8_WAIT_L(0); PG8_BAR; PG8_MMA(1, 0, At, B0); PG8_MMA(1, 1, At, B1); PG8_BAR; PG8_SCHED;
;             PG8_LDB(B0, 1, 0); PG8_LDB(B1, 1, 1); PG8_SCHED; PG8_LDA(At, 1, 0); PG8_STAGE(PG8_SA(0, 1), a2 + hstep, voffA);
;             PG8_WAIT_V(8); PG8_WAIT_L(0); PG8_BAR; PG8_MMA(0, 0, At, B0); PG8_MMA(0, 1, At, B1); PG8_BAR; PG8_SCHED;
	s_setprio 1
	s_waitcnt lgkmcnt(0)
	v_mfma_f32_16x16x32_bf16 v[32:35], v[148:151], v[190:193], v[32:35]
	v_mfma_f32_16x16x32_bf16 v[24:27], v[166:169], v[190:193], v[24:27]
	v_mfma_f32_16x16x32_bf16 v[20:23], v[148:151], v[198:201], v[20:23]
	v_mfma_f32_16x16x32_bf16 v[16:19], v[166:169], v[198:201], v[16:19]
	v_mfma_f32_16x16x32_bf16 v[12:15], v[148:151], v[206:209], v[12:15]
	v_mfma_f32_16x16x32_bf16 v[8:11], v[166:169], v[206:209], v[8:11]
	v_mfma_f32_16x16x32_bf16 v[4:7], v[148:151], v[214:217], v[4:7]
	v_mfma_f32_16x16x32_bf16 v[0:3], v[166:169], v[214:217], v[0:3]
	v_mfma_f32_16x16x32_bf16 v[32:35], v[162:165], v[194:197], v[32:35]
	v_mfma_f32_16x16x32_bf16 v[24:27], v[170:173], v[194:197], v[24:27]
	v_mfma_f32_16x16x32_bf16 v[20:23], v[162:165], v[202:205], v[20:23]
	v_mfma_f32_16x16x32_bf16 v[16:19], v[170:173], v[202:205], v[16:19]
	v_mfma_f32_16x16x32_bf16 v[12:15], v[162:165], v[210:213], v[12:15]
	v_mfma_f32_16x16x32_bf16 v[8:11], v[170:173], v[210:213], v[8:11]
	v_mfma_f32_16x16x32_bf16 v[4:7], v[162:165], v[218:221], v[4:7]
	v_mfma_f32_16x16x32_bf16 v[0:3], v[170:173], v[218:221], v[0:3]
	s_setprio 0
	s_setprio 1
	v_mfma_f32_16x16x32_bf16 v[92:95], v[174:177], v[190:193], v[92:95]
	v_mfma_f32_16x16x32_bf16 v[88:91], v[182:185], v[190:193], v[88:91]
	v_mfma_f32_16x16x32_bf16 v[84:87], v[174:177], v[198:201], v[84:87]
	v_mfma_f32_16x16x32_bf16 v[80:83], v[182:185], v[198:201], v[80:83]
	v_mfma_f32_16x16x32_bf16 v[56:59], v[174:177], v[206:209], v[56:59]
	v_mfma_f32_16x16x32_bf16 v[48:51], v[182:185], v[206:209], v[48:51]
	v_mfma_f32_16x16x32_bf16 v[36:39], v[174:177], v[214:217], v[36:39]
	v_mfma_f32_16x16x32_bf16 v[28:31], v[182:185], v[214:217], v[28:31]
	v_mfma_f32_16x16x32_bf16 v[92:95], v[178:181], v[194:197], v[92:95]
	v_mfma_f32_16x16x32_bf16 v[88:91], v[186:189], v[194:197], v[88:91]
	v_mfma_f32_16x16x32_bf16 v[84:87], v[178:181], v[202:205], v[84:87]
	v_mfma_f32_16x16x32_bf16 v[80:83], v[186:189], v[202:205], v[80:83]
	v_mfma_f32_16x16x32_bf16 v[56:59], v[178:181], v[210:213], v[56:59]
	v_mfma_f32_16x16x32_bf16 v[48:51], v[186:189], v[210:213], v[48:51]
	v_mfma_f32_16x16x32_bf16 v[36:39], v[178:181], v[218:221], v[36:39]
	v_mfma_f32_16x16x32_bf16 v[28:31], v[186:189], v[218:221], v[28:31]
	s_setprio 0
	s_barrier
	s_add_i32 s36, 0, 0x18000
	v_add_u32_e32 v161, s36, v154
	s_add_i32 s37, 0, 0x1c000
	ds_read_b128 v[148:151], v156 offset:32768
	ds_read_b128 v[162:165], v157 offset:32768
	ds_read_b128 v[166:169], v156 offset:34816
	ds_read_b128 v[170:173], v157 offset:34816
	v_add_u32_e32 v161, s37, v154
	ds_read_b128 v[174:177], v156 offset:49152
	ds_read_b128 v[178:181], v157 offset:49152
	ds_read_b128 v[182:185], v156 offset:51200
	ds_read_b128 v[186:189], v157 offset:51200
	s_add_u32 s52, s52, 0x80000
	s_addc_u32 s53, s53, 0
	s_mov_b32 m0, s62
	v_lshl_add_u64 v[228:229], s[52:53], 0, v[134:135]
	ds_read_b128 v[190:193], v158 offset:32768
	ds_read_b128 v[194:197], v242 offset:32768
	ds_read_b128 v[198:201], v158 offset:34816
	ds_read_b128 v[202:205], v242 offset:34816
	ds_read_b128 v[206:209], v158 offset:36864
	ds_read_b128 v[210:213], v242 offset:36864
	ds_read_b128 v[214:217], v158 offset:38912
	ds_read_b128 v[218:221], v242 offset:38912
	global_load_lds_dwordx4 v[228:229], off
	v_lshl_add_u64 v[228:229], s[52:53], 0, v[130:131]
	s_mov_b32 m0, s63
	s_nop 0
	global_load_lds_dwordx4 v[228:229], off
	s_waitcnt vmcnt(8)
	s_waitcnt lgkmcnt(0)
	s_barrier
	s_setprio 1
	s_waitcnt lgkmcnt(0)
	v_mfma_f32_16x16x32_bf16 v[76:79], v[148:151], v[190:193], v[76:79]
	v_mfma_f32_16x16x32_bf16 v[72:75], v[166:169], v[190:193], v[72:75]
	v_mfma_f32_16x16x32_bf16 v[68:71], v[148:151], v[198:201], v[68:71]
	v_mfma_f32_16x16x32_bf16 v[64:67], v[166:169], v[198:201], v[64:67]
	v_mfma_f32_16x16x32_bf16 v[60:63], v[148:151], v[206:209], v[60:63]
	v_mfma_f32_16x16x32_bf16 v[52:55], v[166:169], v[206:209], v[52:55]
	v_mfma_f32_16x16x32_bf16 v[44:47], v[148:151], v[214:217], v[44:47]
	v_mfma_f32_16x16x32_bf16 v[40:43], v[166:169], v[214:217], v[40:43]
	v_mfma_f32_16x16x32_bf16 v[76:79], v[162:165], v[194:197], v[76:79]
	v_mfma_f32_16x16x32_bf16 v[72:75], v[170:173], v[194:197], v[72:75]
	v_mfma_f32_16x16x32_bf16 v[68:71], v[162:165], v[202:205], v[68:71]
	v_mfma_f32_16x16x32_bf16 v[64:67], v[170:173], v[202:205], v[64:67]
	v_mfma_f32_16x16x32_bf16 v[60:63], v[162:165], v[210:213], v[60:63]
	v_mfma_f32_16x16x32_bf16 v[52:55], v[170:173], v[210:213], v[52:55]
	v_mfma_f32_16x16x32_bf16 v[44:47], v[162:165], v[218:221], v[44:47]
	v_mfma_f32_16x16x32_bf16 v[40:43], v[170:173], v[218:221], v[40:43]
	s_setprio 0
	s_setprio 1
	v_mfma_f32_16x16x32_bf16 v[124:127], v[174:177], v[190:193], v[124:127]
	v_mfma_f32_16x16x32_bf16 v[120:123], v[182:185], v[190:193], v[120:123]
	v_mfma_f32_16x16x32_bf16 v[116:119], v[174:177], v[198:201], v[116:119]
	v_mfma_f32_16x16x32_bf16 v[112:115], v[182:185], v[198:201], v[112:115]
	v_mfma_f32_16x16x32_bf16 v[108:111], v[174:177], v[206:209], v[108:111]
	v_mfma_f32_16x16x32_bf16 v[104:107], v[182:185], v[206:209], v[104:107]
	v_mfma_f32_16x16x32_bf16 v[100:103], v[174:177], v[214:217], v[100:103]
	v_mfma_f32_16x16x32_bf16 v[96:99], v[182:185], v[214:217], v[96:99]
	v_mfma_f32_16x16x32_bf16 v[124:127], v[178:181], v[194:197], v[124:127]
	v_mfma_f32_16x16x32_bf16 v[120:123], v[186:189], v[194:197], v[120:123]
	v_mfma_f32_16x16x32_bf16 v[116:119], v[178:181], v[202:205], v[116:119]
	v_mfma_f32_16x16x32_bf16 v[112:115], v[186:189], v[202:205], v[112:115]
	v_mfma_f32_16x16x32_bf16 v[108:111], v[178:181], v[210:213], v[108:111]
	v_mfma_f32_16x16x32_bf16 v[104:107], v[186:189], v[210:213], v[104:107]
	v_mfma_f32_16x16x32_bf16 v[100:103], v[178:181], v[218:221], v[100:103]
	v_mfma_f32_16x16x32_bf16 v[96:99], v[186:189], v[218:221], v[96:99]
	s_setprio 0
	s_barrier
; #define PG8_STAGE(bufoff, gbase, voff) do { _Pragma("unroll") for (int _i = 0; _i < 2; ++_i) \
;         __builtin_amdgcn_global_load_lds((const unsigned*)((const char*)(gbase) + (voff)[_i]), (PG8_LAS unsigned*)(lds + (bufoff) + ldsw + _i * 8192), 16, 0, 0); } while (0)
; #define PG8_LDA(dst, b, h) do { _Pragma("unroll") for (int m = 0; m < 4; ++m) _Pragma("unroll") for (int k = 0; k < 2; ++k) dst[m][k] = *(const PG8_LAS bf16x8*)(lds + PG8_SA(b, h) + aoff + m * 2048 + k * 1024); } while (0)
; #define PG8_MMA(ai, bj, At, Bt) do { __builtin_amdgcn_s_setprio(1); _Pragma("unroll") for (int m = 0; m < 4; ++m) _Pragma("unroll") for (int n = 0; n < 2; ++n) _Pragma("unroll") for (int k = 0; k < 2; ++k) \
;         acc[ai][bj][m][n] = __builtin_amdgcn_mfma_f32_16x16x32_bf16(Bt[n][k], At[m][k], acc[ai][bj][m][n], 0, 0, 0); __builtin_amdgcn_s_setprio(0); } while (0)
; #define PG8_WAIT_V(n) asm volatile("s_waitcnt vmcnt(" #n ")" ::: "memory")
; #define PG8_WAIT_L(n) asm volatile("s_waitcnt lgkmcnt(" #n ")" ::: "memory")
; #define PG8_BAR __builtin_amdgcn_s_barrier()
; #define PG8_SCHED __builtin_amdgcn_sched_barrier(0)
; template <class Epi, class Sched, bool ALIGN_EPI = false, bool SP2 = false>
; __device__ __forceinline__ void gemm_phase(PG8_LAS unsigned char* lds, const Gemm g, const Sched& S, const Epi& E) {
;     ...
;         for (int t = 0; t < nt; t += 2) {
;             const bool last = (t == nt - 2);
;     ...
;             PG8_LDA(At, 1, 1); PG8_STAGE(PG8_SB(1, 0), b3, voffB); PG8_STAGE(PG8_SB(1, 1), b3 + hstep, voffB); PG8_STAGE(PG8_SA(1, 0), a3, voffA);
;             PG8_WAIT_V(8); PG8_WAIT_L(0); PG8_BAR; PG8_MMA(1, 0, At, B0); PG8_MMA(1, 1, At, B1); PG8_BAR; PG8_SCHED;
	s_add_i32 s36, s36, s57
	v_lshl_add_u64 v[152:153], v[152:153], 0, s[12:13]
	s_mov_b32 m0, s36
	ds_read_b128 v[190:193], v158 offset:49152
	ds_read_b128 v[194:197], v242 offset:49152
	ds_read_b128 v[198:201], v158 offset:51200
	ds_read_b128 v[202:205], v242 offset:51200
	ds_read_b128 v[206:209], v158 offset:53248
	ds_read_b128 v[210:213], v242 offset:53248
	ds_read_b128 v[214:217], v158 offset:55296
	ds_read_b128 v[218:221], v242 offset:55296
	global_load_lds_dwordx4 v[152:153], off
	s_add_i32 m0, s36, 0x2000
	s_add_u32 s50, s50, 0x80080
	v_lshl_add_u64 v[152:153], v[222:223], 0, s[12:13]
	s_addc_u32 s51, s51, 0
	s_add_i32 s36, s37, s57
	global_load_lds_dwordx4 v[152:153], off
	v_lshl_add_u64 v[152:153], s[50:51], 0, v[132:133]
	s_mov_b32 m0, s36
	s_nop 0
	global_load_lds_dwordx4 v[152:153], off
	v_lshl_add_u64 v[152:153], s[50:51], 0, v[128:129]
	s_add_i32 m0, s36, 0x2000
	s_nop 0
	global_load_lds_dwordx4 v[152:153], off
	v_lshl_add_u64 v[152:153], v[224:225], 0, s[12:13]
	s_mov_b32 m0, s65
	s_nop 0
	global_load_lds_dwordx4 v[152:153], off
	v_lshl_add_u64 v[152:153], v[226:227], 0, s[12:13]
	s_mov_b32 m0, s66
	s_nop 0
	global_load_lds_dwordx4 v[152:153], off
	s_waitcnt vmcnt(8)
	s_waitcnt lgkmcnt(0)
	s_barrier
	s_setprio 1
	s_waitcnt lgkmcnt(0)
	v_mfma_f32_16x16x32_bf16 v[32:35], v[148:151], v[190:193], v[32:35]
	v_mfma_f32_16x16x32_bf16 v[24:27], v[166:169], v[190:193], v[24:27]
	v_mfma_f32_16x16x32_bf16 v[20:23], v[148:151], v[198:201], v[20:23]
	v_mfma_f32_16x16x32_bf16 v[16:19], v[166:169], v[198:201], v[16:19]
	v_mfma_f32_16x16x32_bf16 v[12:15], v[148:151], v[206:209], v[12:15]
	v_mfma_f32_16x16x32_bf16 v[8:11], v[166:169], v[206:209], v[8:11]
	v_mfma_f32_16x16x32_bf16 v[4:7], v[148:151], v[214:217], v[4:7]
	v_mfma_f32_16x16x32_bf16 v[0:3], v[166:169], v[214:217], v[0:3]
	v_mfma_f32_16x16x32_bf16 v[32:35], v[162:165], v[194:197], v[32:35]
	v_mfma_f32_16x16x32_bf16 v[24:27], v[170:173], v[194:197], v[24:27]
	v_mfma_f32_16x16x32_bf16 v[20:23], v[162:165], v[202:205], v[20:23]
	v_mfma_f32_16x16x32_bf16 v[16:19], v[170:173], v[202:205], v[16:19]
	v_mfma_f32_16x16x32_bf16 v[12:15], v[162:165], v[210:213], v[12:15]
	v_mfma_f32_16x16x32_bf16 v[8:11], v[170:173], v[210:213], v[8:11]
	v_mfma_f32_16x16x32_bf16 v[4:7], v[162:165], v[218:221], v[4:7]
	v_mfma_f32_16x16x32_bf16 v[0:3], v[170:173], v[218:221], v[0:3]
	s_setprio 0
	s_setprio 1
	v_mfma_f32_16x16x32_bf16 v[92:95], v[174:177], v[190:193], v[92:95]
	v_mfma_f32_16x16x32_bf16 v[88:91], v[182:185], v[190:193], v[88:91]
	v_mfma_f32_16x16x32_bf16 v[84:87], v[174:177], v[198:201], v[84:87]
	v_mfma_f32_16x16x32_bf16 v[80:83], v[182:185], v[198:201], v[80:83]
	v_mfma_f32_16x16x32_bf16 v[56:59], v[174:177], v[206:209], v[56:59]
	v_mfma_f32_16x16x32_bf16 v[48:51], v[182:185], v[206:209], v[48:51]
	v_mfma_f32_16x16x32_bf16 v[36:39], v[174:177], v[214:217], v[36:39]
	v_mfma_f32_16x16x32_bf16 v[28:31], v[182:185], v[214:217], v[28:31]
	v_mfma_f32_16x16x32_bf16 v[92:95], v[178:181], v[194:197], v[92:95]
	v_mfma_f32_16x16x32_bf16 v[88:91], v[186:189], v[194:197], v[88:91]
	v_mfma_f32_16x16x32_bf16 v[84:87], v[178:181], v[202:205], v[84:87]
	v_mfma_f32_16x16x32_bf16 v[80:83], v[186:189], v[202:205], v[80:83]
	v_mfma_f32_16x16x32_bf16 v[56:59], v[178:181], v[210:213], v[56:59]
	v_mfma_f32_16x16x32_bf16 v[48:51], v[186:189], v[210:213], v[48:51]
	v_mfma_f32_16x16x32_bf16 v[36:39], v[178:181], v[218:221], v[36:39]
	v_mfma_f32_16x16x32_bf16 v[28:31], v[186:189], v[218:221], v[28:31]
	s_setprio 0
	s_barrier
	s_add_i32 s73, s73, 2
	s_add_u32 s48, s48, 0x100
	s_addc_u32 s49, s49, 0
	s_add_u32 s71, s71, 0x100
	s_addc_u32 s72, s72, 0
	s_cmp_gt_u32 s73, 29
	s_cbranch_scc0 .LBB0_131
	s_and_b64 vcc, exec, s[14:15]
	s_cbranch_vccz .LBB0_138
	s_barrier
	v_lshl_add_u32 v148, s46, 8, v145
	s_cmp_lg_u32 s70, 44
	s_mov_b64 s[46:47], -1
	s_cbranch_scc1 .LBB0_139
